# P11 PLE-gate epilogue rewritten by hand: residual/projection tiles loaded two units ahead (3 register buffers, counted vmcnt), sigmoid with packed f32 mul/add/fma, running 64-bit pointers
# baseline (speedup 1.0000x reference)
.LBB0_170:
	v_lshlrev_b64 v[142:143], 11, v[146:147]
	v_lshl_add_u64 v[150:151], s[38:39], 0, v[142:143]
	v_lshl_add_u64 v[160:161], s[92:93], 0, v[142:143]
	v_lshlrev_b64 v[142:143], 1, v[144:145]
	v_lshl_add_u64 v[150:151], v[150:151], 0, v[142:143]
	v_lshl_add_u64 v[160:161], v[160:161], 0, v[142:143]
	v_lshlrev_b64 v[144:145], 2, v[144:145]
	v_lshlrev_b64 v[162:163], 12, v[146:147]
	v_lshl_add_u64 v[162:163], s[88:89], 0, v[162:163]
	v_lshl_add_u64 v[162:163], v[162:163], 0, v[144:145]
	global_load_dwordx4 v[168:171], v[150:151], off
	global_load_dwordx4 v[172:175], v[160:161], off
	global_load_dwordx4 v[176:179], v[150:151], off offset:256
	global_load_dwordx4 v[180:183], v[160:161], off offset:256
	s_waitcnt vmcnt(4)
	v_fmamk_f32 v166, v242, 0x3a800000, v194
	v_rsq_f32_e32 v166, v166
	s_nop 0
	v_mul_f32_e32 v166, 0xbfb8aa3b, v166
	s_mov_b64 vcc, 0x8000
	s_nop 0
	v_lshl_add_u64 v[150:151], v[150:151], 0, vcc
	v_lshl_add_u64 v[160:161], v[160:161], 0, vcc
	global_load_dwordx4 v[220:223], v[150:151], off
	global_load_dwordx4 v[224:227], v[160:161], off
	s_waitcnt vmcnt(4)
	v_pk_mul_f32 v[184:185], v[126:127], v[166:167] op_sel_hi:[1,0]
	v_pk_mul_f32 v[186:187], v[128:129], v[166:167] op_sel_hi:[1,0]
	v_pk_mul_f32 v[188:189], v[122:123], v[166:167] op_sel_hi:[1,0]
	v_pk_mul_f32 v[190:191], v[124:125], v[166:167] op_sel_hi:[1,0]
	v_exp_f32_e32 v184, v184
	v_exp_f32_e32 v185, v185
	v_exp_f32_e32 v186, v186
	v_exp_f32_e32 v187, v187
	v_exp_f32_e32 v188, v188
	v_exp_f32_e32 v189, v189
	v_exp_f32_e32 v190, v190
	v_exp_f32_e32 v191, v191
	v_lshlrev_b32_e32 v230, 16, v168
	v_and_b32_e32 v231, 0xffff0000, v168
	v_lshlrev_b32_e32 v232, 16, v169
	v_and_b32_e32 v233, 0xffff0000, v169
	v_lshlrev_b32_e32 v234, 16, v170
	v_and_b32_e32 v235, 0xffff0000, v170
	v_lshlrev_b32_e32 v236, 16, v171
	v_and_b32_e32 v237, 0xffff0000, v171
	v_pk_add_f32 v[184:185], v[184:185], 1.0 op_sel_hi:[1,0]
	v_pk_add_f32 v[186:187], v[186:187], 1.0 op_sel_hi:[1,0]
	v_pk_add_f32 v[188:189], v[188:189], 1.0 op_sel_hi:[1,0]
	v_pk_add_f32 v[190:191], v[190:191], 1.0 op_sel_hi:[1,0]
	v_rcp_f32_e32 v184, v184
	v_rcp_f32_e32 v185, v185
	v_rcp_f32_e32 v186, v186
	v_rcp_f32_e32 v187, v187
	v_rcp_f32_e32 v188, v188
	v_rcp_f32_e32 v189, v189
	v_rcp_f32_e32 v190, v190
	v_rcp_f32_e32 v191, v191
	v_lshlrev_b32_e32 v214, 16, v172
	v_and_b32_e32 v215, 0xffff0000, v172
	v_lshlrev_b32_e32 v216, 16, v173
	v_and_b32_e32 v217, 0xffff0000, v173
	v_lshlrev_b32_e32 v218, 16, v174
	v_and_b32_e32 v219, 0xffff0000, v174
	v_lshlrev_b32_e32 v238, 16, v175
	v_and_b32_e32 v239, 0xffff0000, v175
	v_pk_fma_f32 v[184:185], v[184:185], v[214:215], v[230:231]
	v_pk_fma_f32 v[186:187], v[186:187], v[216:217], v[232:233]
	v_pk_fma_f32 v[188:189], v[188:189], v[218:219], v[234:235]
	v_pk_fma_f32 v[190:191], v[190:191], v[238:239], v[236:237]
	global_store_dwordx4 v[162:163], v[184:187], off
	global_store_dwordx4 v[162:163], v[188:191], off offset:16
	s_nop 1
	global_load_dwordx4 v[168:171], v[150:151], off offset:256
	global_load_dwordx4 v[172:175], v[160:161], off offset:256
	s_waitcnt vmcnt(6)
	v_pk_mul_f32 v[184:185], v[118:119], v[166:167] op_sel_hi:[1,0]
	v_pk_mul_f32 v[186:187], v[120:121], v[166:167] op_sel_hi:[1,0]
	v_pk_mul_f32 v[188:189], v[114:115], v[166:167] op_sel_hi:[1,0]
	v_pk_mul_f32 v[190:191], v[116:117], v[166:167] op_sel_hi:[1,0]
	v_exp_f32_e32 v184, v184
	v_exp_f32_e32 v185, v185
	v_exp_f32_e32 v186, v186
	v_exp_f32_e32 v187, v187
	v_exp_f32_e32 v188, v188
	v_exp_f32_e32 v189, v189
	v_exp_f32_e32 v190, v190
	v_exp_f32_e32 v191, v191
	v_lshlrev_b32_e32 v230, 16, v176
	v_and_b32_e32 v231, 0xffff0000, v176
	v_lshlrev_b32_e32 v232, 16, v177
	v_and_b32_e32 v233, 0xffff0000, v177
	v_lshlrev_b32_e32 v234, 16, v178
	v_and_b32_e32 v235, 0xffff0000, v178
	v_lshlrev_b32_e32 v236, 16, v179
	v_and_b32_e32 v237, 0xffff0000, v179
	v_pk_add_f32 v[184:185], v[184:185], 1.0 op_sel_hi:[1,0]
	v_pk_add_f32 v[186:187], v[186:187], 1.0 op_sel_hi:[1,0]
	v_pk_add_f32 v[188:189], v[188:189], 1.0 op_sel_hi:[1,0]
	v_pk_add_f32 v[190:191], v[190:191], 1.0 op_sel_hi:[1,0]
	v_rcp_f32_e32 v184, v184
	v_rcp_f32_e32 v185, v185
	v_rcp_f32_e32 v186, v186
	v_rcp_f32_e32 v187, v187
	v_rcp_f32_e32 v188, v188
	v_rcp_f32_e32 v189, v189
	v_rcp_f32_e32 v190, v190
	v_rcp_f32_e32 v191, v191
	v_lshlrev_b32_e32 v214, 16, v180
	v_and_b32_e32 v215, 0xffff0000, v180
	v_lshlrev_b32_e32 v216, 16, v181
	v_and_b32_e32 v217, 0xffff0000, v181
	v_lshlrev_b32_e32 v218, 16, v182
	v_and_b32_e32 v219, 0xffff0000, v182
	v_lshlrev_b32_e32 v238, 16, v183
	v_and_b32_e32 v239, 0xffff0000, v183
	v_fmamk_f32 v228, v243, 0x3a800000, v194
	v_rsq_f32_e32 v228, v228
	s_nop 0
	v_mul_f32_e32 v228, 0xbfb8aa3b, v228
	v_pk_fma_f32 v[184:185], v[184:185], v[214:215], v[230:231]
	v_pk_fma_f32 v[186:187], v[186:187], v[216:217], v[232:233]
	v_pk_fma_f32 v[188:189], v[188:189], v[218:219], v[234:235]
	v_pk_fma_f32 v[190:191], v[190:191], v[238:239], v[236:237]
	global_store_dwordx4 v[162:163], v[184:187], off offset:512
	global_store_dwordx4 v[162:163], v[188:191], off offset:528
	s_nop 1
	s_mov_b64 vcc, 0x10000
	s_nop 0
	v_lshl_add_u64 v[162:163], v[162:163], 0, vcc
	s_mov_b64 vcc, 0x8000
	s_nop 0
	v_lshl_add_u64 v[150:151], v[150:151], 0, vcc
	v_lshl_add_u64 v[160:161], v[160:161], 0, vcc
	global_load_dwordx4 v[176:179], v[150:151], off
	global_load_dwordx4 v[180:183], v[160:161], off
	s_waitcnt vmcnt(8)
	v_pk_mul_f32 v[184:185], v[110:111], v[228:229] op_sel_hi:[1,0]
	v_pk_mul_f32 v[186:187], v[112:113], v[228:229] op_sel_hi:[1,0]
	v_pk_mul_f32 v[188:189], v[106:107], v[228:229] op_sel_hi:[1,0]
	v_pk_mul_f32 v[190:191], v[108:109], v[228:229] op_sel_hi:[1,0]
	v_exp_f32_e32 v184, v184
	v_exp_f32_e32 v185, v185
	v_exp_f32_e32 v186, v186
	v_exp_f32_e32 v187, v187
	v_exp_f32_e32 v188, v188
	v_exp_f32_e32 v189, v189
	v_exp_f32_e32 v190, v190
	v_exp_f32_e32 v191, v191
	v_lshlrev_b32_e32 v230, 16, v220
	v_and_b32_e32 v231, 0xffff0000, v220
	v_lshlrev_b32_e32 v232, 16, v221
	v_and_b32_e32 v233, 0xffff0000, v221
	v_lshlrev_b32_e32 v234, 16, v222
	v_and_b32_e32 v235, 0xffff0000, v222
	v_lshlrev_b32_e32 v236, 16, v223
	v_and_b32_e32 v237, 0xffff0000, v223
	v_pk_add_f32 v[184:185], v[184:185], 1.0 op_sel_hi:[1,0]
	v_pk_add_f32 v[186:187], v[186:187], 1.0 op_sel_hi:[1,0]
	v_pk_add_f32 v[188:189], v[188:189], 1.0 op_sel_hi:[1,0]
	v_pk_add_f32 v[190:191], v[190:191], 1.0 op_sel_hi:[1,0]
	v_rcp_f32_e32 v184, v184
	v_rcp_f32_e32 v185, v185
	v_rcp_f32_e32 v186, v186
	v_rcp_f32_e32 v187, v187
	v_rcp_f32_e32 v188, v188
	v_rcp_f32_e32 v189, v189
	v_rcp_f32_e32 v190, v190
	v_rcp_f32_e32 v191, v191
	v_lshlrev_b32_e32 v214, 16, v224
	v_and_b32_e32 v215, 0xffff0000, v224
	v_lshlrev_b32_e32 v216, 16, v225
	v_and_b32_e32 v217, 0xffff0000, v225
	v_lshlrev_b32_e32 v218, 16, v226
	v_and_b32_e32 v219, 0xffff0000, v226
	v_lshlrev_b32_e32 v238, 16, v227
	v_and_b32_e32 v239, 0xffff0000, v227
	v_pk_fma_f32 v[184:185], v[184:185], v[214:215], v[230:231]
	v_pk_fma_f32 v[186:187], v[186:187], v[216:217], v[232:233]
	v_pk_fma_f32 v[188:189], v[188:189], v[218:219], v[234:235]
	v_pk_fma_f32 v[190:191], v[190:191], v[238:239], v[236:237]
	global_store_dwordx4 v[162:163], v[184:187], off
	global_store_dwordx4 v[162:163], v[188:191], off offset:16
	s_nop 1
	global_load_dwordx4 v[220:223], v[150:151], off offset:256
	global_load_dwordx4 v[224:227], v[160:161], off offset:256
	s_waitcnt vmcnt(8)
	v_pk_mul_f32 v[184:185], v[102:103], v[228:229] op_sel_hi:[1,0]
	v_pk_mul_f32 v[186:187], v[104:105], v[228:229] op_sel_hi:[1,0]
	v_pk_mul_f32 v[188:189], v[98:99], v[228:229] op_sel_hi:[1,0]
	v_pk_mul_f32 v[190:191], v[100:101], v[228:229] op_sel_hi:[1,0]
	v_exp_f32_e32 v184, v184
	v_exp_f32_e32 v185, v185
	v_exp_f32_e32 v186, v186
	v_exp_f32_e32 v187, v187
	v_exp_f32_e32 v188, v188
	v_exp_f32_e32 v189, v189
	v_exp_f32_e32 v190, v190
	v_exp_f32_e32 v191, v191
	v_lshlrev_b32_e32 v230, 16, v168
	v_and_b32_e32 v231, 0xffff0000, v168
	v_lshlrev_b32_e32 v232, 16, v169
	v_and_b32_e32 v233, 0xffff0000, v169
	v_lshlrev_b32_e32 v234, 16, v170
	v_and_b32_e32 v235, 0xffff0000, v170
	v_lshlrev_b32_e32 v236, 16, v171
	v_and_b32_e32 v237, 0xffff0000, v171
	v_pk_add_f32 v[184:185], v[184:185], 1.0 op_sel_hi:[1,0]
	v_pk_add_f32 v[186:187], v[186:187], 1.0 op_sel_hi:[1,0]
	v_pk_add_f32 v[188:189], v[188:189], 1.0 op_sel_hi:[1,0]
	v_pk_add_f32 v[190:191], v[190:191], 1.0 op_sel_hi:[1,0]
	v_rcp_f32_e32 v184, v184
	v_rcp_f32_e32 v185, v185
	v_rcp_f32_e32 v186, v186
	v_rcp_f32_e32 v187, v187
	v_rcp_f32_e32 v188, v188
	v_rcp_f32_e32 v189, v189
	v_rcp_f32_e32 v190, v190
	v_rcp_f32_e32 v191, v191
	v_lshlrev_b32_e32 v214, 16, v172
	v_and_b32_e32 v215, 0xffff0000, v172
	v_lshlrev_b32_e32 v216, 16, v173
	v_and_b32_e32 v217, 0xffff0000, v173
	v_lshlrev_b32_e32 v218, 16, v174
	v_and_b32_e32 v219, 0xffff0000, v174
	v_lshlrev_b32_e32 v238, 16, v175
	v_and_b32_e32 v239, 0xffff0000, v175
	v_fmamk_f32 v166, v244, 0x3a800000, v194
	v_rsq_f32_e32 v166, v166
	s_nop 0
	v_mul_f32_e32 v166, 0xbfb8aa3b, v166
	v_pk_fma_f32 v[184:185], v[184:185], v[214:215], v[230:231]
	v_pk_fma_f32 v[186:187], v[186:187], v[216:217], v[232:233]
	v_pk_fma_f32 v[188:189], v[188:189], v[218:219], v[234:235]
	v_pk_fma_f32 v[190:191], v[190:191], v[238:239], v[236:237]
	global_store_dwordx4 v[162:163], v[184:187], off offset:512
	global_store_dwordx4 v[162:163], v[188:191], off offset:528
	s_nop 1
	s_mov_b64 vcc, 0x10000
	s_nop 0
	v_lshl_add_u64 v[162:163], v[162:163], 0, vcc
	s_mov_b64 vcc, 0x8000
	s_nop 0
	v_lshl_add_u64 v[150:151], v[150:151], 0, vcc
	v_lshl_add_u64 v[160:161], v[160:161], 0, vcc
	global_load_dwordx4 v[168:171], v[150:151], off
	global_load_dwordx4 v[172:175], v[160:161], off
	s_waitcnt vmcnt(8)
	v_pk_mul_f32 v[184:185], v[94:95], v[166:167] op_sel_hi:[1,0]
	v_pk_mul_f32 v[186:187], v[96:97], v[166:167] op_sel_hi:[1,0]
	v_pk_mul_f32 v[188:189], v[90:91], v[166:167] op_sel_hi:[1,0]
	v_pk_mul_f32 v[190:191], v[92:93], v[166:167] op_sel_hi:[1,0]
	v_exp_f32_e32 v184, v184
	v_exp_f32_e32 v185, v185
	v_exp_f32_e32 v186, v186
	v_exp_f32_e32 v187, v187
	v_exp_f32_e32 v188, v188
	v_exp_f32_e32 v189, v189
	v_exp_f32_e32 v190, v190
	v_exp_f32_e32 v191, v191
	v_lshlrev_b32_e32 v230, 16, v176
	v_and_b32_e32 v231, 0xffff0000, v176
	v_lshlrev_b32_e32 v232, 16, v177
	v_and_b32_e32 v233, 0xffff0000, v177
	v_lshlrev_b32_e32 v234, 16, v178
	v_and_b32_e32 v235, 0xffff0000, v178
	v_lshlrev_b32_e32 v236, 16, v179
	v_and_b32_e32 v237, 0xffff0000, v179
	v_pk_add_f32 v[184:185], v[184:185], 1.0 op_sel_hi:[1,0]
	v_pk_add_f32 v[186:187], v[186:187], 1.0 op_sel_hi:[1,0]
	v_pk_add_f32 v[188:189], v[188:189], 1.0 op_sel_hi:[1,0]
	v_pk_add_f32 v[190:191], v[190:191], 1.0 op_sel_hi:[1,0]
	v_rcp_f32_e32 v184, v184
	v_rcp_f32_e32 v185, v185
	v_rcp_f32_e32 v186, v186
	v_rcp_f32_e32 v187, v187
	v_rcp_f32_e32 v188, v188
	v_rcp_f32_e32 v189, v189
	v_rcp_f32_e32 v190, v190
	v_rcp_f32_e32 v191, v191
	v_lshlrev_b32_e32 v214, 16, v180
	v_and_b32_e32 v215, 0xffff0000, v180
	v_lshlrev_b32_e32 v216, 16, v181
	v_and_b32_e32 v217, 0xffff0000, v181
	v_lshlrev_b32_e32 v218, 16, v182
	v_and_b32_e32 v219, 0xffff0000, v182
	v_lshlrev_b32_e32 v238, 16, v183
	v_and_b32_e32 v239, 0xffff0000, v183
	v_pk_fma_f32 v[184:185], v[184:185], v[214:215], v[230:231]
	v_pk_fma_f32 v[186:187], v[186:187], v[216:217], v[232:233]
	v_pk_fma_f32 v[188:189], v[188:189], v[218:219], v[234:235]
	v_pk_fma_f32 v[190:191], v[190:191], v[238:239], v[236:237]
	global_store_dwordx4 v[162:163], v[184:187], off
	global_store_dwordx4 v[162:163], v[188:191], off offset:16
	s_nop 1
	global_load_dwordx4 v[176:179], v[150:151], off offset:256
	global_load_dwordx4 v[180:183], v[160:161], off offset:256
	s_waitcnt vmcnt(8)
	v_pk_mul_f32 v[184:185], v[86:87], v[166:167] op_sel_hi:[1,0]
	v_pk_mul_f32 v[186:187], v[88:89], v[166:167] op_sel_hi:[1,0]
	v_pk_mul_f32 v[188:189], v[82:83], v[166:167] op_sel_hi:[1,0]
	v_pk_mul_f32 v[190:191], v[84:85], v[166:167] op_sel_hi:[1,0]
	v_exp_f32_e32 v184, v184
	v_exp_f32_e32 v185, v185
	v_exp_f32_e32 v186, v186
	v_exp_f32_e32 v187, v187
	v_exp_f32_e32 v188, v188
	v_exp_f32_e32 v189, v189
	v_exp_f32_e32 v190, v190
	v_exp_f32_e32 v191, v191
	v_lshlrev_b32_e32 v230, 16, v220
	v_and_b32_e32 v231, 0xffff0000, v220
	v_lshlrev_b32_e32 v232, 16, v221
	v_and_b32_e32 v233, 0xffff0000, v221
	v_lshlrev_b32_e32 v234, 16, v222
	v_and_b32_e32 v235, 0xffff0000, v222
	v_lshlrev_b32_e32 v236, 16, v223
	v_and_b32_e32 v237, 0xffff0000, v223
	v_pk_add_f32 v[184:185], v[184:185], 1.0 op_sel_hi:[1,0]
	v_pk_add_f32 v[186:187], v[186:187], 1.0 op_sel_hi:[1,0]
	v_pk_add_f32 v[188:189], v[188:189], 1.0 op_sel_hi:[1,0]
	v_pk_add_f32 v[190:191], v[190:191], 1.0 op_sel_hi:[1,0]
	v_rcp_f32_e32 v184, v184
	v_rcp_f32_e32 v185, v185
	v_rcp_f32_e32 v186, v186
	v_rcp_f32_e32 v187, v187
	v_rcp_f32_e32 v188, v188
	v_rcp_f32_e32 v189, v189
	v_rcp_f32_e32 v190, v190
	v_rcp_f32_e32 v191, v191
	v_lshlrev_b32_e32 v214, 16, v224
	v_and_b32_e32 v215, 0xffff0000, v224
	v_lshlrev_b32_e32 v216, 16, v225
	v_and_b32_e32 v217, 0xffff0000, v225
	v_lshlrev_b32_e32 v218, 16, v226
	v_and_b32_e32 v219, 0xffff0000, v226
	v_lshlrev_b32_e32 v238, 16, v227
	v_and_b32_e32 v239, 0xffff0000, v227
	v_fmamk_f32 v228, v245, 0x3a800000, v194
	v_rsq_f32_e32 v228, v228
	s_nop 0
	v_mul_f32_e32 v228, 0xbfb8aa3b, v228
	v_pk_fma_f32 v[184:185], v[184:185], v[214:215], v[230:231]
	v_pk_fma_f32 v[186:187], v[186:187], v[216:217], v[232:233]
	v_pk_fma_f32 v[188:189], v[188:189], v[218:219], v[234:235]
	v_pk_fma_f32 v[190:191], v[190:191], v[238:239], v[236:237]
	global_store_dwordx4 v[162:163], v[184:187], off offset:512
	global_store_dwordx4 v[162:163], v[188:191], off offset:528
	s_nop 1
	s_mov_b64 vcc, 0x10000
	s_nop 0
	v_lshl_add_u64 v[162:163], v[162:163], 0, vcc
	s_mov_b64 vcc, 0x28000
	s_nop 0
	v_lshl_add_u64 v[150:151], v[150:151], 0, vcc
	v_lshl_add_u64 v[160:161], v[160:161], 0, vcc
	global_load_dwordx4 v[220:223], v[150:151], off
	global_load_dwordx4 v[224:227], v[160:161], off
	s_waitcnt vmcnt(8)
	v_pk_mul_f32 v[184:185], v[76:77], v[228:229] op_sel_hi:[1,0]
	v_pk_mul_f32 v[186:187], v[78:79], v[228:229] op_sel_hi:[1,0]
	v_pk_mul_f32 v[188:189], v[72:73], v[228:229] op_sel_hi:[1,0]
	v_pk_mul_f32 v[190:191], v[74:75], v[228:229] op_sel_hi:[1,0]
	v_exp_f32_e32 v184, v184
	v_exp_f32_e32 v185, v185
	v_exp_f32_e32 v186, v186
	v_exp_f32_e32 v187, v187
	v_exp_f32_e32 v188, v188
	v_exp_f32_e32 v189, v189
	v_exp_f32_e32 v190, v190
	v_exp_f32_e32 v191, v191
	v_lshlrev_b32_e32 v230, 16, v168
	v_and_b32_e32 v231, 0xffff0000, v168
	v_lshlrev_b32_e32 v232, 16, v169
	v_and_b32_e32 v233, 0xffff0000, v169
	v_lshlrev_b32_e32 v234, 16, v170
	v_and_b32_e32 v235, 0xffff0000, v170
	v_lshlrev_b32_e32 v236, 16, v171
	v_and_b32_e32 v237, 0xffff0000, v171
	v_pk_add_f32 v[184:185], v[184:185], 1.0 op_sel_hi:[1,0]
	v_pk_add_f32 v[186:187], v[186:187], 1.0 op_sel_hi:[1,0]
	v_pk_add_f32 v[188:189], v[188:189], 1.0 op_sel_hi:[1,0]
	v_pk_add_f32 v[190:191], v[190:191], 1.0 op_sel_hi:[1,0]
	v_rcp_f32_e32 v184, v184
	v_rcp_f32_e32 v185, v185
	v_rcp_f32_e32 v186, v186
	v_rcp_f32_e32 v187, v187
	v_rcp_f32_e32 v188, v188
	v_rcp_f32_e32 v189, v189
	v_rcp_f32_e32 v190, v190
	v_rcp_f32_e32 v191, v191
	v_lshlrev_b32_e32 v214, 16, v172
	v_and_b32_e32 v215, 0xffff0000, v172
	v_lshlrev_b32_e32 v216, 16, v173
	v_and_b32_e32 v217, 0xffff0000, v173
	v_lshlrev_b32_e32 v218, 16, v174
	v_and_b32_e32 v219, 0xffff0000, v174
	v_lshlrev_b32_e32 v238, 16, v175
	v_and_b32_e32 v239, 0xffff0000, v175
	v_pk_fma_f32 v[184:185], v[184:185], v[214:215], v[230:231]
	v_pk_fma_f32 v[186:187], v[186:187], v[216:217], v[232:233]
	v_pk_fma_f32 v[188:189], v[188:189], v[218:219], v[234:235]
	v_pk_fma_f32 v[190:191], v[190:191], v[238:239], v[236:237]
	global_store_dwordx4 v[162:163], v[184:187], off
	global_store_dwordx4 v[162:163], v[188:191], off offset:16
	s_nop 1
	global_load_dwordx4 v[168:171], v[150:151], off offset:256
	global_load_dwordx4 v[172:175], v[160:161], off offset:256
	s_waitcnt vmcnt(8)
	v_pk_mul_f32 v[184:185], v[68:69], v[228:229] op_sel_hi:[1,0]
	v_pk_mul_f32 v[186:187], v[70:71], v[228:229] op_sel_hi:[1,0]
	v_pk_mul_f32 v[188:189], v[64:65], v[228:229] op_sel_hi:[1,0]
	v_pk_mul_f32 v[190:191], v[66:67], v[228:229] op_sel_hi:[1,0]
	v_exp_f32_e32 v184, v184
	v_exp_f32_e32 v185, v185
	v_exp_f32_e32 v186, v186
	v_exp_f32_e32 v187, v187
	v_exp_f32_e32 v188, v188
	v_exp_f32_e32 v189, v189
	v_exp_f32_e32 v190, v190
	v_exp_f32_e32 v191, v191
	v_lshlrev_b32_e32 v230, 16, v176
	v_and_b32_e32 v231, 0xffff0000, v176
	v_lshlrev_b32_e32 v232, 16, v177
	v_and_b32_e32 v233, 0xffff0000, v177
	v_lshlrev_b32_e32 v234, 16, v178
	v_and_b32_e32 v235, 0xffff0000, v178
	v_lshlrev_b32_e32 v236, 16, v179
	v_and_b32_e32 v237, 0xffff0000, v179
	v_pk_add_f32 v[184:185], v[184:185], 1.0 op_sel_hi:[1,0]
	v_pk_add_f32 v[186:187], v[186:187], 1.0 op_sel_hi:[1,0]
	v_pk_add_f32 v[188:189], v[188:189], 1.0 op_sel_hi:[1,0]
	v_pk_add_f32 v[190:191], v[190:191], 1.0 op_sel_hi:[1,0]
	v_rcp_f32_e32 v184, v184
	v_rcp_f32_e32 v185, v185
	v_rcp_f32_e32 v186, v186
	v_rcp_f32_e32 v187, v187
	v_rcp_f32_e32 v188, v188
	v_rcp_f32_e32 v189, v189
	v_rcp_f32_e32 v190, v190
	v_rcp_f32_e32 v191, v191
	v_lshlrev_b32_e32 v214, 16, v180
	v_and_b32_e32 v215, 0xffff0000, v180
	v_lshlrev_b32_e32 v216, 16, v181
	v_and_b32_e32 v217, 0xffff0000, v181
	v_lshlrev_b32_e32 v218, 16, v182
	v_and_b32_e32 v219, 0xffff0000, v182
	v_lshlrev_b32_e32 v238, 16, v183
	v_and_b32_e32 v239, 0xffff0000, v183
	v_fmamk_f32 v166, v246, 0x3a800000, v194
	v_rsq_f32_e32 v166, v166
	s_nop 0
	v_mul_f32_e32 v166, 0xbfb8aa3b, v166
	v_pk_fma_f32 v[184:185], v[184:185], v[214:215], v[230:231]
	v_pk_fma_f32 v[186:187], v[186:187], v[216:217], v[232:233]
	v_pk_fma_f32 v[188:189], v[188:189], v[218:219], v[234:235]
	v_pk_fma_f32 v[190:191], v[190:191], v[238:239], v[236:237]
	global_store_dwordx4 v[162:163], v[184:187], off offset:512
	global_store_dwordx4 v[162:163], v[188:191], off offset:528
	s_nop 1
	s_mov_b64 vcc, 0x50000
	s_nop 0
	v_lshl_add_u64 v[162:163], v[162:163], 0, vcc
	s_mov_b64 vcc, 0x8000
	s_nop 0
	v_lshl_add_u64 v[150:151], v[150:151], 0, vcc
	v_lshl_add_u64 v[160:161], v[160:161], 0, vcc
	global_load_dwordx4 v[176:179], v[150:151], off
	global_load_dwordx4 v[180:183], v[160:161], off
	s_waitcnt vmcnt(8)
	v_pk_mul_f32 v[184:185], v[60:61], v[166:167] op_sel_hi:[1,0]
	v_pk_mul_f32 v[186:187], v[62:63], v[166:167] op_sel_hi:[1,0]
	v_pk_mul_f32 v[188:189], v[56:57], v[166:167] op_sel_hi:[1,0]
	v_pk_mul_f32 v[190:191], v[58:59], v[166:167] op_sel_hi:[1,0]
	v_exp_f32_e32 v184, v184
	v_exp_f32_e32 v185, v185
	v_exp_f32_e32 v186, v186
	v_exp_f32_e32 v187, v187
	v_exp_f32_e32 v188, v188
	v_exp_f32_e32 v189, v189
	v_exp_f32_e32 v190, v190
	v_exp_f32_e32 v191, v191
	v_lshlrev_b32_e32 v230, 16, v220
	v_and_b32_e32 v231, 0xffff0000, v220
	v_lshlrev_b32_e32 v232, 16, v221
	v_and_b32_e32 v233, 0xffff0000, v221
	v_lshlrev_b32_e32 v234, 16, v222
	v_and_b32_e32 v235, 0xffff0000, v222
	v_lshlrev_b32_e32 v236, 16, v223
	v_and_b32_e32 v237, 0xffff0000, v223
	v_pk_add_f32 v[184:185], v[184:185], 1.0 op_sel_hi:[1,0]
	v_pk_add_f32 v[186:187], v[186:187], 1.0 op_sel_hi:[1,0]
	v_pk_add_f32 v[188:189], v[188:189], 1.0 op_sel_hi:[1,0]
	v_pk_add_f32 v[190:191], v[190:191], 1.0 op_sel_hi:[1,0]
	v_rcp_f32_e32 v184, v184
	v_rcp_f32_e32 v185, v185
	v_rcp_f32_e32 v186, v186
	v_rcp_f32_e32 v187, v187
	v_rcp_f32_e32 v188, v188
	v_rcp_f32_e32 v189, v189
	v_rcp_f32_e32 v190, v190
	v_rcp_f32_e32 v191, v191
	v_lshlrev_b32_e32 v214, 16, v224
	v_and_b32_e32 v215, 0xffff0000, v224
	v_lshlrev_b32_e32 v216, 16, v225
	v_and_b32_e32 v217, 0xffff0000, v225
	v_lshlrev_b32_e32 v218, 16, v226
	v_and_b32_e32 v219, 0xffff0000, v226
	v_lshlrev_b32_e32 v238, 16, v227
	v_and_b32_e32 v239, 0xffff0000, v227
	v_pk_fma_f32 v[184:185], v[184:185], v[214:215], v[230:231]
	v_pk_fma_f32 v[186:187], v[186:187], v[216:217], v[232:233]
	v_pk_fma_f32 v[188:189], v[188:189], v[218:219], v[234:235]
	v_pk_fma_f32 v[190:191], v[190:191], v[238:239], v[236:237]
	global_store_dwordx4 v[162:163], v[184:187], off
	global_store_dwordx4 v[162:163], v[188:191], off offset:16
	s_nop 1
	global_load_dwordx4 v[220:223], v[150:151], off offset:256
	global_load_dwordx4 v[224:227], v[160:161], off offset:256
	s_waitcnt vmcnt(8)
	v_pk_mul_f32 v[184:185], v[52:53], v[166:167] op_sel_hi:[1,0]
	v_pk_mul_f32 v[186:187], v[54:55], v[166:167] op_sel_hi:[1,0]
	v_pk_mul_f32 v[188:189], v[48:49], v[166:167] op_sel_hi:[1,0]
	v_pk_mul_f32 v[190:191], v[50:51], v[166:167] op_sel_hi:[1,0]
	v_exp_f32_e32 v184, v184
	v_exp_f32_e32 v185, v185
	v_exp_f32_e32 v186, v186
	v_exp_f32_e32 v187, v187
	v_exp_f32_e32 v188, v188
	v_exp_f32_e32 v189, v189
	v_exp_f32_e32 v190, v190
	v_exp_f32_e32 v191, v191
	v_lshlrev_b32_e32 v230, 16, v168
	v_and_b32_e32 v231, 0xffff0000, v168
	v_lshlrev_b32_e32 v232, 16, v169
	v_and_b32_e32 v233, 0xffff0000, v169
	v_lshlrev_b32_e32 v234, 16, v170
	v_and_b32_e32 v235, 0xffff0000, v170
	v_lshlrev_b32_e32 v236, 16, v171
	v_and_b32_e32 v237, 0xffff0000, v171
	v_pk_add_f32 v[184:185], v[184:185], 1.0 op_sel_hi:[1,0]
	v_pk_add_f32 v[186:187], v[186:187], 1.0 op_sel_hi:[1,0]
	v_pk_add_f32 v[188:189], v[188:189], 1.0 op_sel_hi:[1,0]
	v_pk_add_f32 v[190:191], v[190:191], 1.0 op_sel_hi:[1,0]
	v_rcp_f32_e32 v184, v184
	v_rcp_f32_e32 v185, v185
	v_rcp_f32_e32 v186, v186
	v_rcp_f32_e32 v187, v187
	v_rcp_f32_e32 v188, v188
	v_rcp_f32_e32 v189, v189
	v_rcp_f32_e32 v190, v190
	v_rcp_f32_e32 v191, v191
	v_lshlrev_b32_e32 v214, 16, v172
	v_and_b32_e32 v215, 0xffff0000, v172
	v_lshlrev_b32_e32 v216, 16, v173
	v_and_b32_e32 v217, 0xffff0000, v173
	v_lshlrev_b32_e32 v218, 16, v174
	v_and_b32_e32 v219, 0xffff0000, v174
	v_lshlrev_b32_e32 v238, 16, v175
	v_and_b32_e32 v239, 0xffff0000, v175
	v_fmamk_f32 v228, v247, 0x3a800000, v194
	v_rsq_f32_e32 v228, v228
	s_nop 0
	v_mul_f32_e32 v228, 0xbfb8aa3b, v228
	v_pk_fma_f32 v[184:185], v[184:185], v[214:215], v[230:231]
	v_pk_fma_f32 v[186:187], v[186:187], v[216:217], v[232:233]
	v_pk_fma_f32 v[188:189], v[188:189], v[218:219], v[234:235]
	v_pk_fma_f32 v[190:191], v[190:191], v[238:239], v[236:237]
	global_store_dwordx4 v[162:163], v[184:187], off offset:512
	global_store_dwordx4 v[162:163], v[188:191], off offset:528
	s_nop 1
	s_mov_b64 vcc, 0x10000
	s_nop 0
	v_lshl_add_u64 v[162:163], v[162:163], 0, vcc
	s_mov_b64 vcc, 0x8000
	s_nop 0
	v_lshl_add_u64 v[150:151], v[150:151], 0, vcc
	v_lshl_add_u64 v[160:161], v[160:161], 0, vcc
	global_load_dwordx4 v[168:171], v[150:151], off
	global_load_dwordx4 v[172:175], v[160:161], off
	s_waitcnt vmcnt(8)
	v_pk_mul_f32 v[184:185], v[44:45], v[228:229] op_sel_hi:[1,0]
	v_pk_mul_f32 v[186:187], v[46:47], v[228:229] op_sel_hi:[1,0]
	v_pk_mul_f32 v[188:189], v[40:41], v[228:229] op_sel_hi:[1,0]
	v_pk_mul_f32 v[190:191], v[42:43], v[228:229] op_sel_hi:[1,0]
	v_exp_f32_e32 v184, v184
	v_exp_f32_e32 v185, v185
	v_exp_f32_e32 v186, v186
	v_exp_f32_e32 v187, v187
	v_exp_f32_e32 v188, v188
	v_exp_f32_e32 v189, v189
	v_exp_f32_e32 v190, v190
	v_exp_f32_e32 v191, v191
	v_lshlrev_b32_e32 v230, 16, v176
	v_and_b32_e32 v231, 0xffff0000, v176
	v_lshlrev_b32_e32 v232, 16, v177
	v_and_b32_e32 v233, 0xffff0000, v177
	v_lshlrev_b32_e32 v234, 16, v178
	v_and_b32_e32 v235, 0xffff0000, v178
	v_lshlrev_b32_e32 v236, 16, v179
	v_and_b32_e32 v237, 0xffff0000, v179
	v_pk_add_f32 v[184:185], v[184:185], 1.0 op_sel_hi:[1,0]
	v_pk_add_f32 v[186:187], v[186:187], 1.0 op_sel_hi:[1,0]
	v_pk_add_f32 v[188:189], v[188:189], 1.0 op_sel_hi:[1,0]
	v_pk_add_f32 v[190:191], v[190:191], 1.0 op_sel_hi:[1,0]
	v_rcp_f32_e32 v184, v184
	v_rcp_f32_e32 v185, v185
	v_rcp_f32_e32 v186, v186
	v_rcp_f32_e32 v187, v187
	v_rcp_f32_e32 v188, v188
	v_rcp_f32_e32 v189, v189
	v_rcp_f32_e32 v190, v190
	v_rcp_f32_e32 v191, v191
	v_lshlrev_b32_e32 v214, 16, v180
	v_and_b32_e32 v215, 0xffff0000, v180
	v_lshlrev_b32_e32 v216, 16, v181
	v_and_b32_e32 v217, 0xffff0000, v181
	v_lshlrev_b32_e32 v218, 16, v182
	v_and_b32_e32 v219, 0xffff0000, v182
	v_lshlrev_b32_e32 v238, 16, v183
	v_and_b32_e32 v239, 0xffff0000, v183
	v_pk_fma_f32 v[184:185], v[184:185], v[214:215], v[230:231]
	v_pk_fma_f32 v[186:187], v[186:187], v[216:217], v[232:233]
	v_pk_fma_f32 v[188:189], v[188:189], v[218:219], v[234:235]
	v_pk_fma_f32 v[190:191], v[190:191], v[238:239], v[236:237]
	global_store_dwordx4 v[162:163], v[184:187], off
	global_store_dwordx4 v[162:163], v[188:191], off offset:16
	s_nop 1
	global_load_dwordx4 v[176:179], v[150:151], off offset:256
	global_load_dwordx4 v[180:183], v[160:161], off offset:256
	s_waitcnt vmcnt(8)
	v_pk_mul_f32 v[184:185], v[36:37], v[228:229] op_sel_hi:[1,0]
	v_pk_mul_f32 v[186:187], v[38:39], v[228:229] op_sel_hi:[1,0]
	v_pk_mul_f32 v[188:189], v[32:33], v[228:229] op_sel_hi:[1,0]
	v_pk_mul_f32 v[190:191], v[34:35], v[228:229] op_sel_hi:[1,0]
	v_exp_f32_e32 v184, v184
	v_exp_f32_e32 v185, v185
	v_exp_f32_e32 v186, v186
	v_exp_f32_e32 v187, v187
	v_exp_f32_e32 v188, v188
	v_exp_f32_e32 v189, v189
	v_exp_f32_e32 v190, v190
	v_exp_f32_e32 v191, v191
	v_lshlrev_b32_e32 v230, 16, v220
	v_and_b32_e32 v231, 0xffff0000, v220
	v_lshlrev_b32_e32 v232, 16, v221
	v_and_b32_e32 v233, 0xffff0000, v221
	v_lshlrev_b32_e32 v234, 16, v222
	v_and_b32_e32 v235, 0xffff0000, v222
	v_lshlrev_b32_e32 v236, 16, v223
	v_and_b32_e32 v237, 0xffff0000, v223
	v_pk_add_f32 v[184:185], v[184:185], 1.0 op_sel_hi:[1,0]
	v_pk_add_f32 v[186:187], v[186:187], 1.0 op_sel_hi:[1,0]
	v_pk_add_f32 v[188:189], v[188:189], 1.0 op_sel_hi:[1,0]
	v_pk_add_f32 v[190:191], v[190:191], 1.0 op_sel_hi:[1,0]
	v_rcp_f32_e32 v184, v184
	v_rcp_f32_e32 v185, v185
	v_rcp_f32_e32 v186, v186
	v_rcp_f32_e32 v187, v187
	v_rcp_f32_e32 v188, v188
	v_rcp_f32_e32 v189, v189
	v_rcp_f32_e32 v190, v190
	v_rcp_f32_e32 v191, v191
	v_lshlrev_b32_e32 v214, 16, v224
	v_and_b32_e32 v215, 0xffff0000, v224
	v_lshlrev_b32_e32 v216, 16, v225
	v_and_b32_e32 v217, 0xffff0000, v225
	v_lshlrev_b32_e32 v218, 16, v226
	v_and_b32_e32 v219, 0xffff0000, v226
	v_lshlrev_b32_e32 v238, 16, v227
	v_and_b32_e32 v239, 0xffff0000, v227
	v_fmamk_f32 v166, v248, 0x3a800000, v194
	v_rsq_f32_e32 v166, v166
	s_nop 0
	v_mul_f32_e32 v166, 0xbfb8aa3b, v166
	v_pk_fma_f32 v[184:185], v[184:185], v[214:215], v[230:231]
	v_pk_fma_f32 v[186:187], v[186:187], v[216:217], v[232:233]
	v_pk_fma_f32 v[188:189], v[188:189], v[218:219], v[234:235]
	v_pk_fma_f32 v[190:191], v[190:191], v[238:239], v[236:237]
	global_store_dwordx4 v[162:163], v[184:187], off offset:512
	global_store_dwordx4 v[162:163], v[188:191], off offset:528
	s_nop 1
	s_mov_b64 vcc, 0x10000
	s_nop 0
	v_lshl_add_u64 v[162:163], v[162:163], 0, vcc
	s_mov_b64 vcc, 0x8000
	s_nop 0
	v_lshl_add_u64 v[150:151], v[150:151], 0, vcc
	v_lshl_add_u64 v[160:161], v[160:161], 0, vcc
	global_load_dwordx4 v[220:223], v[150:151], off
	global_load_dwordx4 v[224:227], v[160:161], off
	s_waitcnt vmcnt(8)
	v_pk_mul_f32 v[184:185], v[28:29], v[166:167] op_sel_hi:[1,0]
	v_pk_mul_f32 v[186:187], v[30:31], v[166:167] op_sel_hi:[1,0]
	v_pk_mul_f32 v[188:189], v[24:25], v[166:167] op_sel_hi:[1,0]
	v_pk_mul_f32 v[190:191], v[26:27], v[166:167] op_sel_hi:[1,0]
	v_exp_f32_e32 v184, v184
	v_exp_f32_e32 v185, v185
	v_exp_f32_e32 v186, v186
	v_exp_f32_e32 v187, v187
	v_exp_f32_e32 v188, v188
	v_exp_f32_e32 v189, v189
	v_exp_f32_e32 v190, v190
	v_exp_f32_e32 v191, v191
	v_lshlrev_b32_e32 v230, 16, v168
	v_and_b32_e32 v231, 0xffff0000, v168
	v_lshlrev_b32_e32 v232, 16, v169
	v_and_b32_e32 v233, 0xffff0000, v169
	v_lshlrev_b32_e32 v234, 16, v170
	v_and_b32_e32 v235, 0xffff0000, v170
	v_lshlrev_b32_e32 v236, 16, v171
	v_and_b32_e32 v237, 0xffff0000, v171
	v_pk_add_f32 v[184:185], v[184:185], 1.0 op_sel_hi:[1,0]
	v_pk_add_f32 v[186:187], v[186:187], 1.0 op_sel_hi:[1,0]
	v_pk_add_f32 v[188:189], v[188:189], 1.0 op_sel_hi:[1,0]
	v_pk_add_f32 v[190:191], v[190:191], 1.0 op_sel_hi:[1,0]
	v_rcp_f32_e32 v184, v184
	v_rcp_f32_e32 v185, v185
	v_rcp_f32_e32 v186, v186
	v_rcp_f32_e32 v187, v187
	v_rcp_f32_e32 v188, v188
	v_rcp_f32_e32 v189, v189
	v_rcp_f32_e32 v190, v190
	v_rcp_f32_e32 v191, v191
	v_lshlrev_b32_e32 v214, 16, v172
	v_and_b32_e32 v215, 0xffff0000, v172
	v_lshlrev_b32_e32 v216, 16, v173
	v_and_b32_e32 v217, 0xffff0000, v173
	v_lshlrev_b32_e32 v218, 16, v174
	v_and_b32_e32 v219, 0xffff0000, v174
	v_lshlrev_b32_e32 v238, 16, v175
	v_and_b32_e32 v239, 0xffff0000, v175
	v_pk_fma_f32 v[184:185], v[184:185], v[214:215], v[230:231]
	v_pk_fma_f32 v[186:187], v[186:187], v[216:217], v[232:233]
	v_pk_fma_f32 v[188:189], v[188:189], v[218:219], v[234:235]
	v_pk_fma_f32 v[190:191], v[190:191], v[238:239], v[236:237]
	global_store_dwordx4 v[162:163], v[184:187], off
	global_store_dwordx4 v[162:163], v[188:191], off offset:16
	s_nop 1
	global_load_dwordx4 v[168:171], v[150:151], off offset:256
	global_load_dwordx4 v[172:175], v[160:161], off offset:256
	s_waitcnt vmcnt(8)
	v_pk_mul_f32 v[184:185], v[20:21], v[166:167] op_sel_hi:[1,0]
	v_pk_mul_f32 v[186:187], v[22:23], v[166:167] op_sel_hi:[1,0]
	v_pk_mul_f32 v[188:189], v[16:17], v[166:167] op_sel_hi:[1,0]
	v_pk_mul_f32 v[190:191], v[18:19], v[166:167] op_sel_hi:[1,0]
	v_exp_f32_e32 v184, v184
	v_exp_f32_e32 v185, v185
	v_exp_f32_e32 v186, v186
	v_exp_f32_e32 v187, v187
	v_exp_f32_e32 v188, v188
	v_exp_f32_e32 v189, v189
	v_exp_f32_e32 v190, v190
	v_exp_f32_e32 v191, v191
	v_lshlrev_b32_e32 v230, 16, v176
	v_and_b32_e32 v231, 0xffff0000, v176
	v_lshlrev_b32_e32 v232, 16, v177
	v_and_b32_e32 v233, 0xffff0000, v177
	v_lshlrev_b32_e32 v234, 16, v178
	v_and_b32_e32 v235, 0xffff0000, v178
	v_lshlrev_b32_e32 v236, 16, v179
	v_and_b32_e32 v237, 0xffff0000, v179
	v_pk_add_f32 v[184:185], v[184:185], 1.0 op_sel_hi:[1,0]
	v_pk_add_f32 v[186:187], v[186:187], 1.0 op_sel_hi:[1,0]
	v_pk_add_f32 v[188:189], v[188:189], 1.0 op_sel_hi:[1,0]
	v_pk_add_f32 v[190:191], v[190:191], 1.0 op_sel_hi:[1,0]
	v_rcp_f32_e32 v184, v184
	v_rcp_f32_e32 v185, v185
	v_rcp_f32_e32 v186, v186
	v_rcp_f32_e32 v187, v187
	v_rcp_f32_e32 v188, v188
	v_rcp_f32_e32 v189, v189
	v_rcp_f32_e32 v190, v190
	v_rcp_f32_e32 v191, v191
	v_lshlrev_b32_e32 v214, 16, v180
	v_and_b32_e32 v215, 0xffff0000, v180
	v_lshlrev_b32_e32 v216, 16, v181
	v_and_b32_e32 v217, 0xffff0000, v181
	v_lshlrev_b32_e32 v218, 16, v182
	v_and_b32_e32 v219, 0xffff0000, v182
	v_lshlrev_b32_e32 v238, 16, v183
	v_and_b32_e32 v239, 0xffff0000, v183
	v_fmamk_f32 v228, v249, 0x3a800000, v194
	v_rsq_f32_e32 v228, v228
	s_nop 0
	v_mul_f32_e32 v228, 0xbfb8aa3b, v228
	v_pk_fma_f32 v[184:185], v[184:185], v[214:215], v[230:231]
	v_pk_fma_f32 v[186:187], v[186:187], v[216:217], v[232:233]
	v_pk_fma_f32 v[188:189], v[188:189], v[218:219], v[234:235]
	v_pk_fma_f32 v[190:191], v[190:191], v[238:239], v[236:237]
	global_store_dwordx4 v[162:163], v[184:187], off offset:512
	global_store_dwordx4 v[162:163], v[188:191], off offset:528
	s_nop 1
	s_mov_b64 vcc, 0x10000
	s_nop 0
	v_lshl_add_u64 v[162:163], v[162:163], 0, vcc
	s_waitcnt vmcnt(6)
	v_pk_mul_f32 v[184:185], v[12:13], v[228:229] op_sel_hi:[1,0]
	v_pk_mul_f32 v[186:187], v[14:15], v[228:229] op_sel_hi:[1,0]
	v_pk_mul_f32 v[188:189], v[8:9], v[228:229] op_sel_hi:[1,0]
	v_pk_mul_f32 v[190:191], v[10:11], v[228:229] op_sel_hi:[1,0]
	v_exp_f32_e32 v184, v184
	v_exp_f32_e32 v185, v185
	v_exp_f32_e32 v186, v186
	v_exp_f32_e32 v187, v187
	v_exp_f32_e32 v188, v188
	v_exp_f32_e32 v189, v189
	v_exp_f32_e32 v190, v190
	v_exp_f32_e32 v191, v191
	v_lshlrev_b32_e32 v230, 16, v220
	v_and_b32_e32 v231, 0xffff0000, v220
	v_lshlrev_b32_e32 v232, 16, v221
	v_and_b32_e32 v233, 0xffff0000, v221
	v_lshlrev_b32_e32 v234, 16, v222
	v_and_b32_e32 v235, 0xffff0000, v222
	v_lshlrev_b32_e32 v236, 16, v223
	v_and_b32_e32 v237, 0xffff0000, v223
	v_pk_add_f32 v[184:185], v[184:185], 1.0 op_sel_hi:[1,0]
	v_pk_add_f32 v[186:187], v[186:187], 1.0 op_sel_hi:[1,0]
	v_pk_add_f32 v[188:189], v[188:189], 1.0 op_sel_hi:[1,0]
	v_pk_add_f32 v[190:191], v[190:191], 1.0 op_sel_hi:[1,0]
	v_rcp_f32_e32 v184, v184
	v_rcp_f32_e32 v185, v185
	v_rcp_f32_e32 v186, v186
	v_rcp_f32_e32 v187, v187
	v_rcp_f32_e32 v188, v188
	v_rcp_f32_e32 v189, v189
	v_rcp_f32_e32 v190, v190
	v_rcp_f32_e32 v191, v191
	v_lshlrev_b32_e32 v214, 16, v224
	v_and_b32_e32 v215, 0xffff0000, v224
	v_lshlrev_b32_e32 v216, 16, v225
	v_and_b32_e32 v217, 0xffff0000, v225
	v_lshlrev_b32_e32 v218, 16, v226
	v_and_b32_e32 v219, 0xffff0000, v226
	v_lshlrev_b32_e32 v238, 16, v227
	v_and_b32_e32 v239, 0xffff0000, v227
	v_pk_fma_f32 v[184:185], v[184:185], v[214:215], v[230:231]
	v_pk_fma_f32 v[186:187], v[186:187], v[216:217], v[232:233]
	v_pk_fma_f32 v[188:189], v[188:189], v[218:219], v[234:235]
	v_pk_fma_f32 v[190:191], v[190:191], v[238:239], v[236:237]
	global_store_dwordx4 v[162:163], v[184:187], off
	global_store_dwordx4 v[162:163], v[188:191], off offset:16
	s_nop 1
	s_waitcnt vmcnt(4)
	v_pk_mul_f32 v[184:185], v[4:5], v[228:229] op_sel_hi:[1,0]
	v_pk_mul_f32 v[186:187], v[6:7], v[228:229] op_sel_hi:[1,0]
	v_pk_mul_f32 v[188:189], v[0:1], v[228:229] op_sel_hi:[1,0]
	v_pk_mul_f32 v[190:191], v[2:3], v[228:229] op_sel_hi:[1,0]
	v_exp_f32_e32 v184, v184
	v_exp_f32_e32 v185, v185
	v_exp_f32_e32 v186, v186
	v_exp_f32_e32 v187, v187
	v_exp_f32_e32 v188, v188
	v_exp_f32_e32 v189, v189
	v_exp_f32_e32 v190, v190
	v_exp_f32_e32 v191, v191
	v_lshlrev_b32_e32 v230, 16, v168
	v_and_b32_e32 v231, 0xffff0000, v168
	v_lshlrev_b32_e32 v232, 16, v169
	v_and_b32_e32 v233, 0xffff0000, v169
	v_lshlrev_b32_e32 v234, 16, v170
	v_and_b32_e32 v235, 0xffff0000, v170
	v_lshlrev_b32_e32 v236, 16, v171
	v_and_b32_e32 v237, 0xffff0000, v171
	v_pk_add_f32 v[184:185], v[184:185], 1.0 op_sel_hi:[1,0]
	v_pk_add_f32 v[186:187], v[186:187], 1.0 op_sel_hi:[1,0]
	v_pk_add_f32 v[188:189], v[188:189], 1.0 op_sel_hi:[1,0]
	v_pk_add_f32 v[190:191], v[190:191], 1.0 op_sel_hi:[1,0]
	v_rcp_f32_e32 v184, v184
	v_rcp_f32_e32 v185, v185
	v_rcp_f32_e32 v186, v186
	v_rcp_f32_e32 v187, v187
	v_rcp_f32_e32 v188, v188
	v_rcp_f32_e32 v189, v189
	v_rcp_f32_e32 v190, v190
	v_rcp_f32_e32 v191, v191
	v_lshlrev_b32_e32 v214, 16, v172
	v_and_b32_e32 v215, 0xffff0000, v172
	v_lshlrev_b32_e32 v216, 16, v173
	v_and_b32_e32 v217, 0xffff0000, v173
	v_lshlrev_b32_e32 v218, 16, v174
	v_and_b32_e32 v219, 0xffff0000, v174
	v_lshlrev_b32_e32 v238, 16, v175
	v_and_b32_e32 v239, 0xffff0000, v175
	v_pk_fma_f32 v[184:185], v[184:185], v[214:215], v[230:231]
	v_pk_fma_f32 v[186:187], v[186:187], v[216:217], v[232:233]
	v_pk_fma_f32 v[188:189], v[188:189], v[218:219], v[234:235]
	v_pk_fma_f32 v[190:191], v[190:191], v[238:239], v[236:237]
	global_store_dwordx4 v[162:163], v[184:187], off offset:512
	global_store_dwordx4 v[162:163], v[188:191], off offset:528
	s_nop 1
	s_andn2_b64 vcc, exec, s[42:43]
	s_cbranch_vccnz .LBB0_159
	s_andn2_b64 vcc, exec, s[0:1]
	s_cbranch_vccnz .LBB0_158
	s_barrier
	s_branch .LBB0_158
